# sample-mixer item: pooling-state row loads hoisted ahead of the GN stage (prologue de-serialisation), on v41
# baseline (speedup 1.0000x reference)
; __device__ __forceinline__ float bflo(unsigned v) { return __uint_as_float(v << 16); }
; __device__ __forceinline__ float bfhi(unsigned v) { return __uint_as_float(v & 0xffff0000u); }
;     __device__ __forceinline__ bf16_t* U() const { return (bf16_t*)(ws + WS_U); }
;     __device__ __forceinline__ bf16_t* P() const { return (bf16_t*)(ws + WS_P); }
;     __device__ __forceinline__ bf16_t* MIX() const { return (bf16_t*)(ws + WS_MIX); }
; __device__ __forceinline__ void mixer_sample_run(const Args& p, int sb, int c2) {
;     const unsigned* U32 = (const unsigned*)p.U(); const unsigned* P32 = (const unsigned*)p.P(); unsigned* M32 = (unsigned*)p.MIX();
;     const size_t rowb = (size_t)NPT + (size_t)sb * DECS;
;     {
;         float w0[31], w1[31];
; #pragma unroll
;         for (int j = 0; j < 31; ++j) { const f32x2v w = *(const f32x2v*)(p.conv_w() + j * 512 + 2 * c2); w0[j] = w.x; w1[j] = w.y; }
;         const f32x2v cb = *(const f32x2v*)(p.conv_b() + 2 * c2);
;         float a0[4], a1[4];
; #pragma unroll
;         for (int t = 0; t < 4; ++t) { a0[t] = cb.x; a1[t] = cb.y; }
; #pragma unroll
;         for (int i = 0; i < 34; ++i) {
;             float x0, x1;
;             if (i < 30) { const f32x2v v = *(const f32x2v*)(p.state_conv() + ((size_t)sb * 30 + i) * 512 + 2 * c2); x0 = v.x; x1 = v.y; }
;             else { const unsigned v = U32[(rowb + (i - 30)) * 256 + c2]; x0 = bflo(v); x1 = bfhi(v); }
; #pragma unroll
;             for (int t = 0; t < 4; ++t) { const int j = i - t; if (j >= 0 && j <= 30) { a0[t] = fmaf(w0[j], x0, a0[t]); a1[t] = fmaf(w1[j], x1, a1[t]); } }
;         }
.LBB0_602:
	s_lshl_b32 s20, s40, 1
	s_cmpk_gt_i32 s40, 0x1ff
	s_mov_b64 s[0:1], -1
	s_cbranch_scc0 .LBB0_604
	s_add_i32 s44, s49, s20
	v_mad_u64_u32 v[102:103], s[0:1], s44, v166, v[66:67]
	global_load_dwordx2 v[98:99], v[2:3], off
	global_load_dwordx2 v[100:101], v[2:3], off offset:2048
	global_load_dwordx2 v[106:107], v[4:5], off
	global_load_dwordx2 v[114:115], v[62:63], off
	v_add_co_u32_e32 v78, vcc, s90, v102
	global_load_dwordx2 v[118:119], v[102:103], off
	global_load_dwordx2 v[120:121], v[102:103], off offset:2048
	v_addc_co_u32_e32 v79, vcc, 0, v103, vcc
	global_load_dwordx2 v[134:135], v[78:79], off offset:-4096
	v_add_co_u32_e32 v80, vcc, s61, v102
	s_mov_b32 s8, 0x8000
	s_nop 0
	v_addc_co_u32_e32 v81, vcc, 0, v103, vcc
	global_load_dwordx2 v[136:137], v[80:81], off offset:2048
	global_load_dwordx2 v[138:139], v[78:79], off
	global_load_dwordx2 v[140:141], v[6:7], off
	global_load_dwordx2 v[142:143], v[8:9], off
	global_load_dwordx2 v[144:145], v[10:11], off
	global_load_dwordx2 v[146:147], v[12:13], off
	global_load_dwordx2 v[148:149], v[14:15], off
	global_load_dwordx2 v[104:105], v[16:17], off
	global_load_dwordx2 v[108:109], v[18:19], off
	global_load_dwordx2 v[110:111], v[20:21], off
	global_load_dwordx2 v[112:113], v[22:23], off
	v_add_co_u32_e32 v80, vcc, s91, v102
	s_mov_b32 s10, 0x9000
	s_nop 0
	v_addc_co_u32_e32 v81, vcc, 0, v103, vcc
	v_add_co_u32_e32 v82, vcc, s82, v102
	s_lshl_b64 s[0:1], s[44:45], 2
	s_nop 0
	v_addc_co_u32_e32 v83, vcc, 0, v103, vcc
	global_load_dwordx2 v[150:151], v[78:79], off offset:2048
	global_load_dwordx2 v[152:153], v[82:83], off offset:-4096
	global_load_dwordx2 v[154:155], v[80:81], off offset:2048
	v_add_co_u32_e32 v78, vcc, s95, v102
	s_waitcnt vmcnt(16)
	v_pk_fma_f32 v[118:119], v[98:99], v[118:119], v[114:115]
	v_addc_co_u32_e32 v79, vcc, 0, v103, vcc
	v_add_co_u32_e32 v80, vcc, s83, v102
	s_waitcnt vmcnt(15)
	v_pk_fma_f32 v[118:119], v[100:101], v[120:121], v[118:119]
	v_addc_co_u32_e32 v81, vcc, 0, v103, vcc
	global_load_dwordx2 v[156:157], v[80:81], off offset:2048
	global_load_dwordx2 v[158:159], v[82:83], off
	global_load_dwordx2 v[160:161], v[82:83], off offset:2048
	global_load_dwordx2 v[162:163], v[78:79], off offset:-4096
	global_load_dwordx2 v[168:169], v[78:79], off
	global_load_dwordx2 v[170:171], v[78:79], off offset:2048
	global_load_dwordx2 v[172:173], v[24:25], off
	global_load_dwordx2 v[174:175], v[26:27], off
	global_load_dwordx2 v[116:117], v[28:29], off
	global_load_dwordx2 v[122:123], v[30:31], off
	global_load_dwordx2 v[124:125], v[32:33], off
	global_load_dwordx2 v[126:127], v[34:35], off
	global_load_dwordx2 v[128:129], v[36:37], off
	global_load_dwordx2 v[130:131], v[38:39], off
	v_add_co_u32_e32 v176, vcc, s8, v102
	v_pk_fma_f32 v[120:121], v[98:99], v[120:121], v[114:115]
	s_nop 0
	v_addc_co_u32_e32 v177, vcc, 0, v103, vcc
	global_load_dwordx2 v[178:179], v[176:177], off offset:-4096
	global_load_dwordx2 v[132:133], v[40:41], off
	global_load_dwordx2 v[90:91], v[42:43], off
	global_load_dwordx2 v[92:93], v[44:45], off
	global_load_dwordx2 v[94:95], v[46:47], off
	global_load_dwordx2 v[96:97], v[48:49], off
	global_load_dwordx2 v[78:79], v[50:51], off
	global_load_dwordx2 v[80:81], v[52:53], off
	global_load_dwordx2 v[82:83], v[54:55], off
	v_add_co_u32_e32 v84, vcc, s92, v102
	s_waitcnt vmcnt(37)
	v_pk_fma_f32 v[118:119], v[106:107], v[134:135], v[118:119]
	v_addc_co_u32_e32 v85, vcc, 0, v103, vcc
	global_load_dwordx2 v[180:181], v[84:85], off offset:2048
	s_nop 0
	global_load_dwordx2 v[84:85], v[56:57], off
	global_load_dwordx2 v[86:87], v[58:59], off
	global_load_dwordx2 v[88:89], v[60:61], off
	v_pk_fma_f32 v[120:121], v[100:101], v[134:135], v[120:121]
	v_pk_fma_f32 v[134:135], v[98:99], v[134:135], v[114:115]
	s_waitcnt vmcnt(40)
	v_pk_fma_f32 v[114:115], v[98:99], v[136:137], v[114:115]
	v_add_co_u32_e32 v98, vcc, s10, v102
	global_load_dwordx2 v[182:183], v[176:177], off
	s_nop 0
	global_load_dwordx2 v[176:177], v[176:177], off offset:2048
	v_addc_co_u32_e32 v99, vcc, 0, v103, vcc
	s_mov_b32 s10, 0xa000
	v_add_co_u32_e32 v184, vcc, s10, v102
	s_mov_b32 s10, 0xb000
	s_nop 0
	v_addc_co_u32_e32 v185, vcc, 0, v103, vcc
	v_add_co_u32_e32 v186, vcc, s10, v102
	s_mov_b32 s10, 0xc000
	s_nop 0
	v_addc_co_u32_e32 v187, vcc, 0, v103, vcc
	v_add_co_u32_e32 v188, vcc, s10, v102
	v_pk_fma_f32 v[134:135], v[100:101], v[136:137], v[134:135]
	s_nop 0
	v_addc_co_u32_e32 v189, vcc, 0, v103, vcc
	global_load_dwordx2 v[190:191], v[184:185], off offset:-4096
	global_load_dwordx2 v[194:195], v[184:185], off
	s_nop 0
	global_load_dwordx2 v[184:185], v[184:185], off offset:2048
	s_nop 0
	global_load_dwordx2 v[196:197], v[188:189], off offset:-4096
	global_load_dwordx2 v[198:199], v[98:99], off offset:2048
	s_nop 0
	global_load_dwordx2 v[186:187], v[186:187], off offset:2048
	s_nop 0
	global_load_dwordx2 v[98:99], v[188:189], off
	s_waitcnt vmcnt(48)
	v_pk_fma_f32 v[100:101], v[100:101], v[138:139], v[114:115]
	v_pk_fma_f32 v[120:121], v[106:107], v[136:137], v[120:121]
	s_waitcnt vmcnt(38)
	v_pk_fma_f32 v[114:115], v[106:107], v[150:151], v[100:101]
	v_pk_fma_f32 v[100:101], v[140:141], v[136:137], v[118:119]
	v_pk_fma_f32 v[134:135], v[106:107], v[138:139], v[134:135]
	v_pk_fma_f32 v[100:101], v[142:143], v[138:139], v[100:101]
	s_mov_b32 s10, 0xe000
	v_pk_fma_f32 v[100:101], v[144:145], v[150:151], v[100:101]
	v_add_co_u32_e32 v136, vcc, s10, v102
	s_waitcnt vmcnt(37)
	v_pk_fma_f32 v[100:101], v[146:147], v[152:153], v[100:101]
	v_addc_co_u32_e32 v137, vcc, 0, v103, vcc
	s_waitcnt vmcnt(36)
; __device__ __forceinline__ float bflo(unsigned v) { return __uint_as_float(v << 16); }
; __device__ __forceinline__ float bfhi(unsigned v) { return __uint_as_float(v & 0xffff0000u); }
; __device__ __forceinline__ void mixer_sample_run(const Args& p, int sb, int c2) {
;     ...
;         for (int i = 0; i < 34; ++i) {
;             float x0, x1;
;             if (i < 30) { const f32x2v v = *(const f32x2v*)(p.state_conv() + ((size_t)sb * 30 + i) * 512 + 2 * c2); x0 = v.x; x1 = v.y; }
;             else { const unsigned v = U32[(rowb + (i - 30)) * 256 + c2]; x0 = bflo(v); x1 = bfhi(v); }
; #pragma unroll
;             for (int t = 0; t < 4; ++t) { const int j = i - t; if (j >= 0 && j <= 30) { a0[t] = fmaf(w0[j], x0, a0[t]); a1[t] = fmaf(w1[j], x1, a1[t]); } }
;         }
	v_pk_fma_f32 v[100:101], v[148:149], v[154:155], v[100:101]
	v_pk_fma_f32 v[114:115], v[140:141], v[152:153], v[114:115]
	s_add_u32 s8, s0, 0x4000
	v_pk_fma_f32 v[114:115], v[142:143], v[154:155], v[114:115]
	s_addc_u32 s9, s1, 0
	s_lshl_b64 s[10:11], s[44:45], 12
	s_lshl_b64 s[12:13], s[8:9], 10
	s_lshl_b64 s[8:9], s[8:9], 11
	s_add_u32 s16, s0, 0x4001
	s_addc_u32 s17, s1, 0
	s_waitcnt vmcnt(34)
	v_pk_fma_f32 v[100:101], v[104:105], v[158:159], v[100:101]
	s_waitcnt vmcnt(33)
	v_pk_fma_f32 v[100:101], v[108:109], v[160:161], v[100:101]
	v_pk_fma_f32 v[114:115], v[144:145], v[158:159], v[114:115]
	s_waitcnt vmcnt(32)
	v_pk_fma_f32 v[106:107], v[110:111], v[162:163], v[100:101]
	global_load_dwordx2 v[100:101], v[188:189], off offset:2048
	v_pk_fma_f32 v[106:107], v[112:113], v[156:157], v[106:107]
	v_pk_fma_f32 v[114:115], v[146:147], v[160:161], v[114:115]
	s_waitcnt vmcnt(30)
	v_pk_fma_f32 v[106:107], v[172:173], v[168:169], v[106:107]
	v_pk_fma_f32 v[114:115], v[148:149], v[162:163], v[114:115]
	s_waitcnt vmcnt(29)
	v_pk_fma_f32 v[118:119], v[174:175], v[170:171], v[106:107]
	v_pk_fma_f32 v[106:107], v[140:141], v[138:139], v[120:121]
	s_nop 0
	v_pk_fma_f32 v[106:107], v[142:143], v[150:151], v[106:107]
	s_nop 0
	v_pk_fma_f32 v[120:121], v[144:145], v[152:153], v[106:107]
	global_load_dwordx2 v[106:107], v[136:137], off offset:-4096
	v_pk_fma_f32 v[120:121], v[146:147], v[154:155], v[120:121]
	s_nop 0
	v_pk_fma_f32 v[120:121], v[148:149], v[158:159], v[120:121]
	s_nop 0
	v_pk_fma_f32 v[120:121], v[104:105], v[160:161], v[120:121]
	s_nop 0
	v_pk_fma_f32 v[120:121], v[108:109], v[162:163], v[120:121]
	s_nop 0
	v_pk_fma_f32 v[120:121], v[110:111], v[156:157], v[120:121]
	s_nop 0
	v_pk_fma_f32 v[120:121], v[112:113], v[168:169], v[120:121]
	s_nop 0
	v_pk_fma_f32 v[120:121], v[172:173], v[170:171], v[120:121]
	s_waitcnt vmcnt(23)
	v_pk_fma_f32 v[138:139], v[174:175], v[178:179], v[120:121]
	v_pk_fma_f32 v[120:121], v[140:141], v[150:151], v[134:135]
	v_lshl_add_u64 v[140:141], v[64:65], 0, s[10:11]
	v_pk_fma_f32 v[120:121], v[142:143], v[152:153], v[120:121]
	s_mov_b32 s10, 0x1000000
	v_pk_fma_f32 v[120:121], v[144:145], v[154:155], v[120:121]
	v_add_co_u32_e32 v140, vcc, s10, v140
	v_pk_fma_f32 v[120:121], v[146:147], v[158:159], v[120:121]
	s_nop 0
	v_addc_co_u32_e32 v141, vcc, 0, v141, vcc
	v_pk_fma_f32 v[120:121], v[148:149], v[160:161], v[120:121]
	s_mov_b32 s10, 0xd000
	v_pk_fma_f32 v[120:121], v[104:105], v[162:163], v[120:121]
	v_pk_fma_f32 v[104:105], v[104:105], v[156:157], v[114:115]
	v_pk_fma_f32 v[120:121], v[108:109], v[156:157], v[120:121]
	v_pk_fma_f32 v[104:105], v[108:109], v[168:169], v[104:105]
	v_pk_fma_f32 v[120:121], v[110:111], v[168:169], v[120:121]
	v_add_co_u32_e32 v102, vcc, s10, v102
	v_pk_fma_f32 v[120:121], v[112:113], v[170:171], v[120:121]
	v_pk_fma_f32 v[104:105], v[110:111], v[170:171], v[104:105]
	v_pk_fma_f32 v[120:121], v[172:173], v[178:179], v[120:121]
	v_addc_co_u32_e32 v103, vcc, 0, v103, vcc
	s_waitcnt vmcnt(14)
	v_pk_fma_f32 v[134:135], v[174:175], v[180:181], v[120:121]
	v_lshl_add_u64 v[120:121], v[64:65], 0, s[12:13]
	global_load_dword v142, v[120:121], off
	global_load_dword v143, v[140:141], off offset:1024
	v_pk_fma_f32 v[104:105], v[112:113], v[178:179], v[104:105]
	global_load_dwordx2 v[112:113], v[102:103], off offset:2048
	global_load_dwordx2 v[108:109], v[136:137], off
	global_load_dwordx2 v[110:111], v[136:137], off offset:2048
	v_pk_fma_f32 v[104:105], v[172:173], v[180:181], v[104:105]
	s_lshl_b64 s[10:11], s[16:17], 11
	s_waitcnt vmcnt(15)
	v_pk_fma_f32 v[102:103], v[174:175], v[182:183], v[104:105]
	v_pk_fma_f32 v[104:105], v[116:117], v[178:179], v[118:119]
	s_waitcnt vmcnt(14)
	v_pk_fma_f32 v[102:103], v[116:117], v[176:177], v[102:103]
	v_pk_fma_f32 v[104:105], v[122:123], v[180:181], v[104:105]
	s_waitcnt vmcnt(13)
	v_pk_fma_f32 v[102:103], v[122:123], v[190:191], v[102:103]
	v_pk_fma_f32 v[104:105], v[124:125], v[182:183], v[104:105]
	s_waitcnt vmcnt(9)
	v_pk_fma_f32 v[102:103], v[124:125], v[198:199], v[102:103]
	v_pk_fma_f32 v[104:105], v[126:127], v[176:177], v[104:105]
	v_pk_fma_f32 v[102:103], v[126:127], v[194:195], v[102:103]
	v_pk_fma_f32 v[104:105], v[128:129], v[190:191], v[104:105]
	v_pk_fma_f32 v[102:103], v[128:129], v[184:185], v[102:103]
	v_pk_fma_f32 v[104:105], v[130:131], v[198:199], v[104:105]
	v_pk_fma_f32 v[102:103], v[130:131], v[196:197], v[102:103]
	v_pk_fma_f32 v[104:105], v[132:133], v[194:195], v[104:105]
	s_add_u32 s18, s0, 0x4002
	v_pk_fma_f32 v[104:105], v[90:91], v[184:185], v[104:105]
	s_addc_u32 s19, s1, 0
	v_pk_fma_f32 v[104:105], v[92:93], v[196:197], v[104:105]
	s_lshl_b64 s[14:15], s[18:19], 11
	s_waitcnt vmcnt(8)
	v_pk_fma_f32 v[104:105], v[94:95], v[186:187], v[104:105]
	s_add_u32 s0, s0, 0x4003
	s_waitcnt vmcnt(7)
	v_pk_fma_f32 v[120:121], v[96:97], v[98:99], v[104:105]
	v_pk_fma_f32 v[104:105], v[116:117], v[180:181], v[138:139]
	s_addc_u32 s1, s1, 0
	v_pk_fma_f32 v[104:105], v[122:123], v[182:183], v[104:105]
	s_waitcnt vmcnt(6)
	v_pk_fma_f32 v[120:121], v[78:79], v[100:101], v[120:121]
	v_pk_fma_f32 v[104:105], v[124:125], v[176:177], v[104:105]
	s_waitcnt vmcnt(5)
	v_pk_fma_f32 v[120:121], v[80:81], v[106:107], v[120:121]
	v_pk_fma_f32 v[104:105], v[126:127], v[190:191], v[104:105]
	s_waitcnt vmcnt(2)
	v_pk_fma_f32 v[120:121], v[82:83], v[112:113], v[120:121]
	v_pk_fma_f32 v[104:105], v[128:129], v[198:199], v[104:105]
	s_waitcnt vmcnt(1)
	v_pk_fma_f32 v[120:121], v[84:85], v[108:109], v[120:121]
	v_pk_fma_f32 v[104:105], v[130:131], v[194:195], v[104:105]
	s_waitcnt vmcnt(0)
; __device__ __forceinline__ void mixer_sample_run(const Args& p, int sb, int c2) {
;     ...
;         const f32x2v gg = *(const f32x2v*)(p.gn_g() + 2 * c2), gb = *(const f32x2v*)(p.gn_b() + 2 * c2);
; #pragma unroll
;         for (int t = 0; t < 4; ++t) gn_swish_store(a0[t], a1[t], gg, gb, M32 + (rowb + t) * 512 + c2);
;     ...
;         for (int i = 0; i < 15; ++i) { const f32x2v v = *(const f32x2v*)(p.state_pool() + ((size_t)sb * 15 + i) * 512 + 2 * c2); q0[i] = v.x; q1[i] = v.y; }
	v_readlane_b32 s62, v242, 31
	v_readlane_b32 s63, v242, 32
	v_lshlrev_b32_e32 v232, 3, v164
	s_mul_i32 s64, s44, 0x7800
	s_nop 2
	s_add_u32 s62, s62, s64
	s_addc_u32 s63, s63, 0
	s_add_u32 s62, s62, 0x1000
	s_addc_u32 s63, s63, 0
	global_load_dwordx2 v[200:201], v232, s[62:63] offset:-4096
	global_load_dwordx2 v[202:203], v232, s[62:63] offset:-2048
	global_load_dwordx2 v[204:205], v232, s[62:63] offset:0
	global_load_dwordx2 v[206:207], v232, s[62:63] offset:2048
	s_add_u32 s62, s62, 0x2000
	s_addc_u32 s63, s63, 0
	global_load_dwordx2 v[208:209], v232, s[62:63] offset:-4096
	global_load_dwordx2 v[210:211], v232, s[62:63] offset:-2048
	global_load_dwordx2 v[212:213], v232, s[62:63] offset:0
	global_load_dwordx2 v[214:215], v232, s[62:63] offset:2048
	s_add_u32 s62, s62, 0x2000
	s_addc_u32 s63, s63, 0
	global_load_dwordx2 v[216:217], v232, s[62:63] offset:-4096
	global_load_dwordx2 v[218:219], v232, s[62:63] offset:-2048
	global_load_dwordx2 v[220:221], v232, s[62:63] offset:0
	global_load_dwordx2 v[222:223], v232, s[62:63] offset:2048
	s_add_u32 s62, s62, 0x2000
	s_addc_u32 s63, s63, 0
	global_load_dwordx2 v[224:225], v232, s[62:63] offset:-4096
	global_load_dwordx2 v[226:227], v232, s[62:63] offset:-2048
	global_load_dwordx2 v[228:229], v232, s[62:63] offset:0
	v_pk_fma_f32 v[120:121], v[86:87], v[110:111], v[120:121]
	v_pk_fma_f32 v[104:105], v[132:133], v[184:185], v[104:105]
	s_nop 0
	v_pk_fma_f32 v[104:105], v[90:91], v[196:197], v[104:105]
	s_nop 0
	v_pk_fma_f32 v[104:105], v[92:93], v[186:187], v[104:105]
	s_nop 0
	v_pk_fma_f32 v[104:105], v[94:95], v[98:99], v[104:105]
	s_nop 0
	v_pk_fma_f32 v[118:119], v[96:97], v[100:101], v[104:105]
	v_pk_fma_f32 v[104:105], v[116:117], v[182:183], v[134:135]
	v_pk_fma_f32 v[116:117], v[132:133], v[186:187], v[102:103]
	v_pk_fma_f32 v[104:105], v[122:123], v[176:177], v[104:105]
	v_lshl_add_u64 v[122:123], v[76:77], 0, s[12:13]
	v_pk_fma_f32 v[104:105], v[124:125], v[190:191], v[104:105]
	s_lshl_b64 s[12:13], s[16:17], 10
	v_pk_fma_f32 v[104:105], v[126:127], v[198:199], v[104:105]
	v_lshl_add_u64 v[124:125], v[76:77], 0, s[12:13]
	v_pk_fma_f32 v[104:105], v[128:129], v[194:195], v[104:105]
	s_lshl_b64 s[12:13], s[18:19], 10
	v_pk_fma_f32 v[104:105], v[130:131], v[184:185], v[104:105]
	v_pk_fma_f32 v[118:119], v[78:79], v[106:107], v[118:119]
	v_pk_fma_f32 v[104:105], v[132:133], v[196:197], v[104:105]
	v_lshl_add_u64 v[126:127], v[76:77], 0, s[12:13]
	v_pk_fma_f32 v[104:105], v[90:91], v[186:187], v[104:105]
	s_lshl_b64 s[12:13], s[0:1], 10
	v_pk_fma_f32 v[104:105], v[92:93], v[98:99], v[104:105]
	v_pk_fma_f32 v[118:119], v[80:81], v[112:113], v[118:119]
	v_pk_fma_f32 v[104:105], v[94:95], v[100:101], v[104:105]
	v_lshl_add_u64 v[128:129], v[76:77], 0, s[12:13]
	v_pk_fma_f32 v[114:115], v[96:97], v[106:107], v[104:105]
	global_load_dword v132, v[140:141], off offset:2048
	global_load_dword v133, v[140:141], off offset:3072
	global_load_dwordx2 v[102:103], v[68:69], off
	global_load_dwordx2 v[104:105], v[70:71], off
	global_load_dword v134, v[122:123], off
	global_load_dword v135, v[124:125], off
	global_load_dword v136, v[126:127], off
	global_load_dword v137, v[128:129], off
	v_and_b32_e32 v127, 64, v165
	v_pk_fma_f32 v[118:119], v[82:83], v[108:109], v[118:119]
	v_lshlrev_b32_e32 v122, 16, v142
	v_and_b32_e32 v123, 0xffff0000, v142
	v_xor_b32_e32 v126, 16, v165
	v_add_u32_e32 v127, 64, v127
	v_pk_fma_f32 v[118:119], v[84:85], v[110:111], v[118:119]
	v_lshlrev_b32_e32 v124, 16, v143
	v_and_b32_e32 v125, 0xffff0000, v143
	v_cmp_lt_i32_e32 vcc, v126, v127
	v_pk_fma_f32 v[118:119], v[86:87], v[122:123], v[118:119]
	v_pk_fma_f32 v[120:121], v[88:89], v[122:123], v[120:121]
	v_cndmask_b32_e32 v126, v165, v126, vcc
	v_pk_fma_f32 v[118:119], v[88:89], v[124:125], v[118:119]
	v_lshlrev_b32_e32 v138, 2, v126
	v_add_f32_e32 v126, v120, v121
	v_add_f32_e32 v128, v118, v119
	v_pk_fma_f32 v[90:91], v[90:91], v[98:99], v[116:117]
	v_add_f32_dpp v126, v126, v126 quad_perm:[1,0,3,2] row_mask:0xf bank_mask:0xf bound_ctrl:1
	v_add_f32_dpp v128, v128, v128 quad_perm:[1,0,3,2] row_mask:0xf bank_mask:0xf bound_ctrl:1
	v_pk_fma_f32 v[90:91], v[92:93], v[100:101], v[90:91]
	v_add_f32_dpp v126, v126, v126 quad_perm:[2,3,0,1] row_mask:0xf bank_mask:0xf bound_ctrl:1
	v_add_f32_dpp v128, v128, v128 quad_perm:[2,3,0,1] row_mask:0xf bank_mask:0xf bound_ctrl:1
	v_pk_fma_f32 v[90:91], v[94:95], v[106:107], v[90:91]
	v_add_f32_dpp v126, v126, v126 row_half_mirror row_mask:0xf bank_mask:0xf bound_ctrl:1
	v_add_f32_dpp v128, v128, v128 row_half_mirror row_mask:0xf bank_mask:0xf bound_ctrl:1
	v_pk_fma_f32 v[92:93], v[96:97], v[112:113], v[90:91]
	v_add_f32_dpp v126, v126, v126 row_mirror row_mask:0xf bank_mask:0xf bound_ctrl:1
	v_add_f32_dpp v128, v128, v128 row_mirror row_mask:0xf bank_mask:0xf bound_ctrl:1
	ds_bpermute_b32 v127, v138, v126
	ds_bpermute_b32 v129, v138, v128
	v_mov_b64_e32 v[94:95], s[60:61]
	v_pk_fma_f32 v[112:113], v[78:79], v[112:113], v[114:115]
	v_pk_fma_f32 v[78:79], v[78:79], v[108:109], v[92:93]
	s_waitcnt lgkmcnt(1)
	v_add_f32_e32 v126, v126, v127
	s_waitcnt lgkmcnt(0)
; __device__ __forceinline__ unsigned pk2(float lo, float hi) { f32x2v v = {lo, hi}; b16x2v b = __builtin_convertvector(v, b16x2v); return __builtin_bit_cast(unsigned, b); }
; __device__ __forceinline__ float fsigmoid(float x) { return __builtin_amdgcn_rcpf(1.0f + __expf(-x)); }
; __device__ __forceinline__ void gn_swish_store(float v0, float v1, f32x2v gg, f32x2v gb, unsigned* dst) {
;     const float mean = half_wave_sum(v0 + v1) * (1.0f / 64.0f); const float d0 = v0 - mean, d1 = v1 - mean;
;     const float rstd = rsqrtf(half_wave_sum(d0 * d0 + d1 * d1) * (1.0f / 64.0f) + LN_EPS);
;     float y0 = d0 * rstd * gg.x + gb.x, y1 = d1 * rstd * gg.y + gb.y;
;     y0 = y0 * fsigmoid(y0); y1 = y1 * fsigmoid(y1);
;     *dst = pk2(y0, y1);
; }
; __device__ __forceinline__ void mixer_sample_run(const Args& p, int sb, int c2) {
;     ...
;         for (int t = 0; t < 4; ++t) gn_swish_store(a0[t], a1[t], gg, gb, M32 + (rowb + t) * 512 + c2);
	v_add_f32_e32 v128, v128, v129
	v_mul_f32_e32 v126, 0x3c800000, v126
	v_mul_f32_e32 v128, 0x3c800000, v128
	v_pk_add_f32 v[120:121], v[120:121], v[126:127] op_sel_hi:[1,0] neg_lo:[0,1] neg_hi:[0,1]
	v_pk_add_f32 v[118:119], v[118:119], v[128:129] op_sel_hi:[1,0] neg_lo:[0,1] neg_hi:[0,1]
	v_pk_mul_f32 v[126:127], v[120:121], v[120:121]
	v_pk_mul_f32 v[128:129], v[118:119], v[118:119]
	v_mov_b32_e32 v131, v126
	v_mov_b32_e32 v130, v128
	v_mov_b32_e32 v126, v129
	v_pk_add_f32 v[126:127], v[130:131], v[126:127]
	v_pk_fma_f32 v[112:113], v[80:81], v[108:109], v[112:113]
	v_pk_fma_f32 v[78:79], v[80:81], v[110:111], v[78:79]
	v_mov_b32_dpp v129, v127 quad_perm:[1,0,3,2] row_mask:0xf bank_mask:0xf bound_ctrl:1
	v_mov_b32_dpp v128, v126 quad_perm:[1,0,3,2] row_mask:0xf bank_mask:0xf bound_ctrl:1
	v_pk_add_f32 v[126:127], v[126:127], v[128:129]
	v_pk_fma_f32 v[112:113], v[82:83], v[110:111], v[112:113]
	v_pk_fma_f32 v[78:79], v[82:83], v[122:123], v[78:79]
	v_mov_b32_dpp v129, v127 quad_perm:[2,3,0,1] row_mask:0xf bank_mask:0xf bound_ctrl:1
	v_mov_b32_dpp v128, v126 quad_perm:[2,3,0,1] row_mask:0xf bank_mask:0xf bound_ctrl:1
	v_pk_add_f32 v[126:127], v[126:127], v[128:129]
	v_pk_fma_f32 v[112:113], v[84:85], v[122:123], v[112:113]
	v_pk_fma_f32 v[78:79], v[84:85], v[124:125], v[78:79]
	v_mov_b32_dpp v129, v127 row_half_mirror row_mask:0xf bank_mask:0xf bound_ctrl:1
	v_mov_b32_dpp v128, v126 row_half_mirror row_mask:0xf bank_mask:0xf bound_ctrl:1
	v_pk_add_f32 v[126:127], v[126:127], v[128:129]
	v_pk_fma_f32 v[112:113], v[86:87], v[124:125], v[112:113]
	s_lshl_b64 s[0:1], s[0:1], 11
	v_mov_b32_dpp v129, v127 row_mirror row_mask:0xf bank_mask:0xf bound_ctrl:1
	v_mov_b32_dpp v128, v126 row_mirror row_mask:0xf bank_mask:0xf bound_ctrl:1
	v_pk_add_f32 v[126:127], v[126:127], v[128:129]
	ds_bpermute_b32 v129, v138, v127
	ds_bpermute_b32 v128, v138, v126
	v_lshl_add_u64 v[116:117], v[72:73], 0, s[8:9]
	s_waitcnt lgkmcnt(0)
	v_pk_add_f32 v[90:91], v[126:127], v[128:129]
	s_nop 0
	v_pk_fma_f32 v[90:91], v[90:91], s[48:49], v[94:95] op_sel_hi:[1,0,0]
	s_waitcnt vmcnt(7)
	v_and_b32_e32 v97, 0xffff0000, v132
	v_mul_f32_e32 v96, 0x4b800000, v91
	v_cmp_gt_f32_e32 vcc, s93, v91
	s_waitcnt vmcnt(6)
	v_lshlrev_b32_e32 v98, 16, v133
	v_cndmask_b32_e32 v91, v91, v96, vcc
	v_rsq_f32_e32 v91, v91
	v_lshlrev_b32_e32 v96, 16, v132
	v_pk_fma_f32 v[78:79], v[86:87], v[96:97], v[78:79]
	v_pk_fma_f32 v[112:113], v[88:89], v[96:97], v[112:113]
	v_mul_f32_e32 v99, 0x45800000, v91
	v_cndmask_b32_e32 v100, v91, v99, vcc
	v_pk_mul_f32 v[100:101], v[120:121], v[100:101] op_sel_hi:[1,0]
	v_add_f32_e32 v114, v112, v113
	s_waitcnt vmcnt(4)
	v_pk_fma_f32 v[100:101], v[102:103], v[100:101], v[104:105]
	v_cmp_gt_f32_e32 vcc, s93, v90
	v_mul_f32_e32 v99, 0xbfb8aa3b, v101
	v_exp_f32_e32 v107, v99
	v_and_b32_e32 v99, 0xffff0000, v133
	v_pk_fma_f32 v[78:79], v[88:89], v[98:99], v[78:79]
	v_mul_f32_e32 v91, 0xbfb8aa3b, v100
	v_add_f32_e32 v80, v78, v79
	v_add_f32_dpp v114, v114, v114 quad_perm:[1,0,3,2] row_mask:0xf bank_mask:0xf bound_ctrl:1
	v_exp_f32_e32 v91, v91
	v_add_f32_dpp v80, v80, v80 quad_perm:[1,0,3,2] row_mask:0xf bank_mask:0xf bound_ctrl:1
	v_add_f32_dpp v114, v114, v114 quad_perm:[2,3,0,1] row_mask:0xf bank_mask:0xf bound_ctrl:1
	s_waitcnt vmcnt(1)
	v_and_b32_e32 v121, 0xffff0000, v136
	v_add_f32_dpp v80, v80, v80 quad_perm:[2,3,0,1] row_mask:0xf bank_mask:0xf bound_ctrl:1
	v_add_f32_dpp v114, v114, v114 row_half_mirror row_mask:0xf bank_mask:0xf bound_ctrl:1
	v_add_f32_e32 v91, 1.0, v91
	v_add_f32_dpp v80, v80, v80 row_half_mirror row_mask:0xf bank_mask:0xf bound_ctrl:1
	v_add_f32_dpp v114, v114, v114 row_mirror row_mask:0xf bank_mask:0xf bound_ctrl:1
	ds_bpermute_b32 v115, v138, v114
	v_add_f32_dpp v84, v80, v80 row_mirror row_mask:0xf bank_mask:0xf bound_ctrl:1
	ds_bpermute_b32 v85, v138, v84
	v_rcp_f32_e32 v106, v91
	v_add_f32_e32 v91, 1.0, v107
	v_rcp_f32_e32 v107, v91
	v_mul_f32_e32 v91, 0x4b800000, v90
	v_cndmask_b32_e32 v90, v90, v91, vcc
	v_rsq_f32_e32 v120, v90
	s_waitcnt lgkmcnt(1)
	v_add_f32_e32 v80, v114, v115
	s_waitcnt lgkmcnt(0)
	v_add_f32_e32 v84, v84, v85
	v_mul_f32_e32 v80, 0x3c800000, v80
	v_mul_f32_e32 v84, 0x3c800000, v84
	v_pk_add_f32 v[82:83], v[112:113], v[80:81] op_sel_hi:[1,0] neg_lo:[0,1] neg_hi:[0,1]
	v_pk_add_f32 v[84:85], v[78:79], v[84:85] op_sel_hi:[1,0] neg_lo:[0,1] neg_hi:[0,1]
	v_pk_mul_f32 v[80:81], v[82:83], v[82:83]
	v_pk_mul_f32 v[78:79], v[84:85], v[84:85]
	v_pk_mul_f32 v[100:101], v[100:101], v[106:107]
	v_mul_f32_e32 v106, 0x45800000, v120
	v_mov_b32_e32 v86, v78
	v_mov_b32_e32 v87, v80
	v_mov_b32_e32 v80, v79
	v_cndmask_b32_e32 v106, v120, v106, vcc
	v_pk_add_f32 v[78:79], v[86:87], v[80:81]
	v_pk_mul_f32 v[106:107], v[118:119], v[106:107] op_sel_hi:[1,0]
	v_cvt_pk_bf16_f32 v120, v100, v101
	v_mov_b32_dpp v81, v79 quad_perm:[1,0,3,2] row_mask:0xf bank_mask:0xf bound_ctrl:1
	v_mov_b32_dpp v80, v78 quad_perm:[1,0,3,2] row_mask:0xf bank_mask:0xf bound_ctrl:1
	v_pk_fma_f32 v[106:107], v[102:103], v[106:107], v[104:105]
	v_pk_add_f32 v[78:79], v[78:79], v[80:81]
	v_mul_f32_e32 v118, 0xbfb8aa3b, v106
	v_mul_f32_e32 v119, 0xbfb8aa3b, v107
	v_mov_b32_dpp v81, v79 quad_perm:[2,3,0,1] row_mask:0xf bank_mask:0xf bound_ctrl:1
	v_mov_b32_dpp v80, v78 quad_perm:[2,3,0,1] row_mask:0xf bank_mask:0xf bound_ctrl:1
	v_exp_f32_e32 v118, v118
	v_exp_f32_e32 v119, v119
	v_pk_add_f32 v[78:79], v[78:79], v[80:81]
	v_lshl_add_u64 v[90:91], v[72:73], 0, s[10:11]
	v_add_f32_e32 v100, 1.0, v118
	v_mov_b32_dpp v81, v79 row_half_mirror row_mask:0xf bank_mask:0xf bound_ctrl:1
	v_mov_b32_dpp v80, v78 row_half_mirror row_mask:0xf bank_mask:0xf bound_ctrl:1
	v_pk_add_f32 v[78:79], v[78:79], v[80:81]
	v_add_f32_e32 v101, 1.0, v119
	v_rcp_f32_e32 v100, v100
	v_mov_b32_dpp v81, v79 row_mirror row_mask:0xf bank_mask:0xf bound_ctrl:1
	v_mov_b32_dpp v80, v78 row_mirror row_mask:0xf bank_mask:0xf bound_ctrl:1
	v_pk_add_f32 v[78:79], v[78:79], v[80:81]
	v_rcp_f32_e32 v101, v101
	ds_bpermute_b32 v81, v138, v79
	ds_bpermute_b32 v80, v138, v78
	global_store_dword v[116:117], v120, off
	v_pk_mul_f32 v[86:87], v[106:107], v[100:101]
	v_lshlrev_b32_e32 v114, 16, v134
	v_cvt_pk_bf16_f32 v86, v86, v87
	s_waitcnt lgkmcnt(0)
; __device__ __forceinline__ unsigned pk2(float lo, float hi) { f32x2v v = {lo, hi}; b16x2v b = __builtin_convertvector(v, b16x2v); return __builtin_bit_cast(unsigned, b); }
; __device__ __forceinline__ float bflo(unsigned v) { return __uint_as_float(v << 16); }
; __device__ __forceinline__ float bfhi(unsigned v) { return __uint_as_float(v & 0xffff0000u); }
; __device__ __forceinline__ void mixer_sample_run(const Args& p, int sb, int c2) {
;     ...
;         for (int i = 0; i < 15; ++i) { const f32x2v v = *(const f32x2v*)(p.state_pool() + ((size_t)sb * 15 + i) * 512 + 2 * c2); q0[i] = v.x; q1[i] = v.y; }
; #pragma unroll
;         for (int t = 0; t < 4; ++t) { const unsigned v = P32[(rowb + t) * 256 + c2]; q0[15 + t] = bflo(v); q1[15 + t] = bfhi(v); }
;         const int w = 2 << (c2 >> 6); const float cnt = (float)w;
; #pragma unroll
;         for (int t = 0; t < 4; ++t) { float s0 = 0.f, s1 = 0.f;
; #pragma unroll
;             for (int i = 0; i < 16; ++i) { if (i < w) { s0 += q0[15 + t - i]; s1 += q1[15 + t - i]; } }
;             M32[(rowb + t) * 512 + 256 + c2] = pk2(s0 / cnt - q0[15 + t], s1 / cnt - q1[15 + t]); }
	v_pk_add_f32 v[78:79], v[78:79], v[80:81]
	global_store_dword v[90:91], v86, off
	v_pk_fma_f32 v[86:87], v[78:79], s[48:49], v[94:95] op_sel_hi:[1,0,0]
	v_lshl_add_u64 v[80:81], v[72:73], 0, s[14:15]
	v_mul_f32_e32 v78, 0x4b800000, v87
	v_cmp_gt_f32_e32 vcc, s93, v87
	v_and_b32_e32 v115, 0xffff0000, v134
	v_pk_add_f32 v[122:123], v[114:115], 0 op_sel_hi:[1,0]
	v_cndmask_b32_e32 v78, v87, v78, vcc
	v_rsq_f32_e32 v87, v78
	v_lshl_add_u64 v[78:79], v[72:73], 0, s[0:1]
	v_lshlrev_b32_e32 v118, 16, v135
	v_and_b32_e32 v119, 0xffff0000, v135
	v_mul_f32_e32 v88, 0x45800000, v87
	v_cndmask_b32_e32 v88, v87, v88, vcc
	v_pk_mul_f32 v[82:83], v[82:83], v[88:89] op_sel_hi:[1,0]
	v_mul_f32_e32 v89, 0x4b800000, v86
	v_pk_fma_f32 v[82:83], v[102:103], v[82:83], v[104:105]
	v_cmp_gt_f32_e32 vcc, s93, v86
	v_mul_f32_e32 v87, 0xbfb8aa3b, v82
	v_mul_f32_e32 v88, 0xbfb8aa3b, v83
	v_cndmask_b32_e32 v86, v86, v89, vcc
	v_exp_f32_e32 v87, v87
	v_exp_f32_e32 v88, v88
	v_rsq_f32_e32 v89, v86
	v_lshlrev_b32_e32 v120, 16, v136
	v_add_f32_e32 v86, 1.0, v87
	v_add_f32_e32 v87, 1.0, v88
	v_mul_f32_e32 v88, 0x45800000, v89
	v_cndmask_b32_e32 v88, v89, v88, vcc
	v_pk_mul_f32 v[84:85], v[84:85], v[88:89] op_sel_hi:[1,0]
	v_rcp_f32_e32 v86, v86
	v_pk_fma_f32 v[84:85], v[102:103], v[84:85], v[104:105]
	v_rcp_f32_e32 v87, v87
	v_mul_f32_e32 v88, 0xbfb8aa3b, v84
	v_mul_f32_e32 v89, 0xbfb8aa3b, v85
	v_exp_f32_e32 v88, v88
	v_exp_f32_e32 v89, v89
	v_pk_mul_f32 v[82:83], v[82:83], v[86:87]
	v_add_f32_e32 v88, 1.0, v88
	v_add_f32_e32 v89, 1.0, v89
	v_rcp_f32_e32 v88, v88
	v_rcp_f32_e32 v89, v89
	v_cvt_pk_bf16_f32 v82, v82, v83
	global_store_dword v[80:81], v82, off
	v_pk_mul_f32 v[82:83], v[84:85], v[88:89]
	s_nop 0
	v_cvt_pk_bf16_f32 v82, v82, v83
	global_store_dword v[78:79], v82, off
	v_mad_u64_u32 v[82:83], s[0:1], s44, v167, v[74:75]
	v_add_co_u32_e32 v84, vcc, s90, v82
	s_nop 1
	v_addc_co_u32_e32 v85, vcc, 0, v83, vcc
	v_add_co_u32_e32 v86, vcc, s82, v82
	s_nop 1
	v_addc_co_u32_e32 v87, vcc, 0, v83, vcc
	v_add_co_u32_e32 v88, vcc, s83, v82
	s_nop 1
	v_addc_co_u32_e32 v89, vcc, 0, v83, vcc
	v_add_co_u32_e32 v92, vcc, s95, v82
	s_nop 1
	v_addc_co_u32_e32 v93, vcc, 0, v83, vcc
	v_add_co_u32_e32 v96, vcc, s92, v82
	v_mov_b32_e32 v94, v226
	v_mov_b32_e32 v95, v227
	s_nop 0
	v_addc_co_u32_e32 v97, vcc, 0, v83, vcc
	v_mov_b32_e32 v88, v222
	v_mov_b32_e32 v89, v223
	s_nop 0
	v_mov_b32_e32 v96, v228
	v_mov_b32_e32 v97, v229
	s_nop 0
	v_mov_b32_e32 v98, v216
	v_mov_b32_e32 v99, v217
	v_mov_b32_e32 v100, v218
	v_mov_b32_e32 v101, v219
	v_mov_b32_e32 v102, v220
	v_mov_b32_e32 v103, v221
	s_nop 0
	v_mov_b32_e32 v92, v224
	v_mov_b32_e32 v93, v225
	v_add_co_u32_e32 v104, vcc, s91, v82
	s_waitcnt vmcnt(4)
	v_pk_add_f32 v[122:123], v[96:97], v[122:123]
	v_addc_co_u32_e32 v105, vcc, 0, v83, vcc
	v_mov_b32_e32 v106, v208
	v_mov_b32_e32 v107, v209
	v_mov_b32_e32 v108, v210
	v_mov_b32_e32 v109, v211
	s_nop 0
	v_mov_b32_e32 v86, v212
	v_mov_b32_e32 v87, v213
	s_nop 0
	v_mov_b32_e32 v104, v214
	v_mov_b32_e32 v105, v215
	v_add_co_u32_e32 v110, vcc, s61, v82
	v_pk_add_f32 v[124:125], v[94:95], v[122:123]
	s_nop 0
	v_addc_co_u32_e32 v111, vcc, 0, v83, vcc
	v_mov_b32_e32 v110, v206
	v_mov_b32_e32 v111, v207
	s_nop 0
	v_mov_b32_e32 v84, v204
	v_mov_b32_e32 v85, v205
	s_nop 0
	v_mov_b32_e32 v112, v202
	v_mov_b32_e32 v113, v203
	s_nop 0
	v_mov_b32_e32 v82, v200
	v_mov_b32_e32 v83, v201
	s_waitcnt vmcnt(8)
	v_pk_add_f32 v[124:125], v[92:93], v[124:125]
	s_nop 0
	v_cndmask_b32_e64 v123, v125, v123, s[2:3]
	v_cndmask_b32_e64 v122, v124, v122, s[2:3]
	v_pk_add_f32 v[124:125], v[88:89], v[122:123]
	s_nop 0
	v_pk_add_f32 v[124:125], v[102:103], v[124:125]
	s_nop 0
	v_pk_add_f32 v[124:125], v[100:101], v[124:125]
	s_nop 0
	v_pk_add_f32 v[124:125], v[98:99], v[124:125]
	s_nop 0
	v_cndmask_b32_e64 v123, v123, v125, s[4:5]
	v_cndmask_b32_e64 v122, v122, v124, s[4:5]
	s_waitcnt vmcnt(4)
	v_pk_add_f32 v[124:125], v[104:105], v[122:123]
	s_nop 0
	v_pk_add_f32 v[124:125], v[86:87], v[124:125]
	s_nop 0
	v_pk_add_f32 v[124:125], v[108:109], v[124:125]
	s_nop 0
	v_pk_add_f32 v[124:125], v[106:107], v[124:125]
	s_waitcnt vmcnt(3)
	v_pk_add_f32 v[124:125], v[110:111], v[124:125]
	s_waitcnt vmcnt(2)
	v_pk_add_f32 v[124:125], v[84:85], v[124:125]
	s_waitcnt vmcnt(1)
	v_pk_add_f32 v[124:125], v[112:113], v[124:125]
	s_waitcnt vmcnt(0)
; __device__ __forceinline__ unsigned pk2(float lo, float hi) { f32x2v v = {lo, hi}; b16x2v b = __builtin_convertvector(v, b16x2v); return __builtin_bit_cast(unsigned, b); }
; __device__ __forceinline__ void mixer_sample_run(const Args& p, int sb, int c2) {
;     ...
;         for (int t = 0; t < 4; ++t) { float s0 = 0.f, s1 = 0.f;
; #pragma unroll
;             for (int i = 0; i < 16; ++i) { if (i < w) { s0 += q0[15 + t - i]; s1 += q1[15 + t - i]; } }
;             M32[(rowb + t) * 512 + 256 + c2] = pk2(s0 / cnt - q0[15 + t], s1 / cnt - q1[15 + t]); }
	v_pk_add_f32 v[82:83], v[82:83], v[124:125]
	v_lshlrev_b32_e32 v124, 16, v137
	v_cndmask_b32_e64 v83, v123, v83, s[6:7]
	v_div_scale_f32 v123, s[0:1], v1, v1, v83
	v_rcp_f32_e32 v126, v123
	v_cndmask_b32_e64 v82, v122, v82, s[6:7]
	v_and_b32_e32 v125, 0xffff0000, v137
	v_fma_f32 v122, -v123, v126, 1.0
	v_fmac_f32_e32 v126, v122, v126
	v_div_scale_f32 v122, vcc, v83, v1, v83
	v_mul_f32_e32 v127, v122, v126
	v_fma_f32 v128, -v123, v127, v122
	v_fmac_f32_e32 v127, v128, v126
	v_fma_f32 v122, -v123, v127, v122
	v_div_scale_f32 v123, s[0:1], v0, v0, v82
	v_rcp_f32_e32 v128, v123
	v_div_fmas_f32 v122, v122, v126, v127
	v_div_fixup_f32 v83, v122, v1, v83
	v_fma_f32 v122, -v123, v128, 1.0
	v_fmac_f32_e32 v128, v122, v128
	v_div_scale_f32 v122, vcc, v82, v0, v82
	v_mul_f32_e32 v126, v122, v128
	v_fma_f32 v127, -v123, v126, v122
	v_fmac_f32_e32 v126, v127, v128
	v_fma_f32 v122, -v123, v126, v122
	v_div_fmas_f32 v122, v122, v128, v126
	v_div_fixup_f32 v82, v122, v0, v82
	v_pk_add_f32 v[122:123], v[118:119], 0 op_sel_hi:[1,0]
	v_pk_add_f32 v[82:83], v[82:83], v[114:115] neg_lo:[0,1] neg_hi:[0,1]
	v_pk_add_f32 v[122:123], v[122:123], v[114:115]
	v_cvt_pk_bf16_f32 v82, v82, v83
	v_pk_add_f32 v[126:127], v[96:97], v[122:123]
	global_store_dword v[116:117], v82, off offset:1024
	v_pk_add_f32 v[126:127], v[94:95], v[126:127]
	s_nop 0
	v_cndmask_b32_e64 v123, v127, v123, s[2:3]
	v_cndmask_b32_e64 v122, v126, v122, s[2:3]
	v_pk_add_f32 v[126:127], v[92:93], v[122:123]
	s_nop 0
	v_pk_add_f32 v[126:127], v[88:89], v[126:127]
	s_nop 0
	v_pk_add_f32 v[126:127], v[102:103], v[126:127]
	s_nop 0
	v_pk_add_f32 v[126:127], v[100:101], v[126:127]
	s_nop 0
	v_cndmask_b32_e64 v123, v123, v127, s[4:5]
	v_cndmask_b32_e64 v122, v122, v126, s[4:5]
	v_pk_add_f32 v[126:127], v[98:99], v[122:123]
	s_nop 0
	v_pk_add_f32 v[126:127], v[104:105], v[126:127]
	s_nop 0
	v_pk_add_f32 v[126:127], v[86:87], v[126:127]
	s_nop 0
	v_pk_add_f32 v[126:127], v[108:109], v[126:127]
	s_nop 0
	v_pk_add_f32 v[126:127], v[106:107], v[126:127]
	s_nop 0
	v_pk_add_f32 v[126:127], v[110:111], v[126:127]
	s_nop 0
	v_pk_add_f32 v[126:127], v[84:85], v[126:127]
	s_nop 0
	v_pk_add_f32 v[112:113], v[112:113], v[126:127]
	s_nop 0
	v_cndmask_b32_e64 v113, v123, v113, s[6:7]
	v_div_scale_f32 v123, s[0:1], v1, v1, v113
	v_rcp_f32_e32 v126, v123
	v_cndmask_b32_e64 v82, v122, v112, s[6:7]
	v_fma_f32 v83, -v123, v126, 1.0
	v_fmac_f32_e32 v126, v83, v126
	v_div_scale_f32 v83, vcc, v113, v1, v113
	v_mul_f32_e32 v112, v83, v126
	v_fma_f32 v116, -v123, v112, v83
	v_fmac_f32_e32 v112, v116, v126
	v_div_scale_f32 v116, s[0:1], v0, v0, v82
	v_rcp_f32_e32 v117, v116
	v_fma_f32 v83, -v123, v112, v83
	v_div_fmas_f32 v83, v83, v126, v112
	v_div_fixup_f32 v83, v83, v1, v113
	v_fma_f32 v112, -v116, v117, 1.0
	v_fmac_f32_e32 v117, v112, v117
	v_div_scale_f32 v112, vcc, v82, v0, v82
	v_mul_f32_e32 v113, v112, v117
	v_fma_f32 v122, -v116, v113, v112
	v_fmac_f32_e32 v113, v122, v117
	v_fma_f32 v112, -v116, v113, v112
	v_div_fmas_f32 v112, v112, v117, v113
	v_div_fixup_f32 v82, v112, v0, v82
	v_pk_add_f32 v[112:113], v[120:121], 0 op_sel_hi:[1,0]
	v_pk_add_f32 v[82:83], v[82:83], v[118:119] neg_lo:[0,1] neg_hi:[0,1]
	v_pk_add_f32 v[112:113], v[112:113], v[118:119]
	v_cvt_pk_bf16_f32 v82, v82, v83
	v_pk_add_f32 v[116:117], v[112:113], v[114:115]
	global_store_dword v[90:91], v82, off offset:1024
	v_pk_add_f32 v[116:117], v[96:97], v[116:117]
	s_nop 0
	v_cndmask_b32_e64 v113, v117, v113, s[2:3]
	v_cndmask_b32_e64 v112, v116, v112, s[2:3]
	v_pk_add_f32 v[116:117], v[94:95], v[112:113]
	s_nop 0
	v_pk_add_f32 v[116:117], v[92:93], v[116:117]
; __device__ __forceinline__ unsigned pk2(float lo, float hi) { f32x2v v = {lo, hi}; b16x2v b = __builtin_convertvector(v, b16x2v); return __builtin_bit_cast(unsigned, b); }
; __device__ __forceinline__ void mixer_sample_run(const Args& p, int sb, int c2) {
;     ...
;         for (int t = 0; t < 4; ++t) { float s0 = 0.f, s1 = 0.f;
; #pragma unroll
;             for (int i = 0; i < 16; ++i) { if (i < w) { s0 += q0[15 + t - i]; s1 += q1[15 + t - i]; } }
;             M32[(rowb + t) * 512 + 256 + c2] = pk2(s0 / cnt - q0[15 + t], s1 / cnt - q1[15 + t]); }
	s_nop 0
	v_pk_add_f32 v[116:117], v[88:89], v[116:117]
	s_nop 0
	v_pk_add_f32 v[116:117], v[102:103], v[116:117]
	s_nop 0
	v_cndmask_b32_e64 v113, v113, v117, s[4:5]
	v_cndmask_b32_e64 v112, v112, v116, s[4:5]
	v_pk_add_f32 v[116:117], v[100:101], v[112:113]
	s_nop 0
	v_pk_add_f32 v[116:117], v[98:99], v[116:117]
	s_nop 0
	v_pk_add_f32 v[116:117], v[104:105], v[116:117]
	s_nop 0
	v_pk_add_f32 v[116:117], v[86:87], v[116:117]
	s_nop 0
	v_pk_add_f32 v[116:117], v[108:109], v[116:117]
	s_nop 0
	v_pk_add_f32 v[116:117], v[106:107], v[116:117]
	s_nop 0
	v_pk_add_f32 v[116:117], v[110:111], v[116:117]
	s_nop 0
	v_pk_add_f32 v[84:85], v[84:85], v[116:117]
	s_nop 0
	v_cndmask_b32_e64 v85, v113, v85, s[6:7]
	v_div_scale_f32 v113, s[0:1], v1, v1, v85
	v_rcp_f32_e32 v116, v113
	v_cndmask_b32_e64 v82, v112, v84, s[6:7]
	v_fma_f32 v83, -v113, v116, 1.0
	v_fmac_f32_e32 v116, v83, v116
	v_div_scale_f32 v83, vcc, v85, v1, v85
	v_mul_f32_e32 v84, v83, v116
	v_fma_f32 v90, -v113, v84, v83
	v_fmac_f32_e32 v84, v90, v116
	v_div_scale_f32 v90, s[0:1], v0, v0, v82
	v_rcp_f32_e32 v91, v90
	v_fma_f32 v83, -v113, v84, v83
	v_div_fmas_f32 v83, v83, v116, v84
	v_div_fixup_f32 v83, v83, v1, v85
	v_fma_f32 v84, -v90, v91, 1.0
	v_fmac_f32_e32 v91, v84, v91
	v_div_scale_f32 v84, vcc, v82, v0, v82
	v_mul_f32_e32 v85, v84, v91
	v_fma_f32 v112, -v90, v85, v84
	v_fmac_f32_e32 v85, v112, v91
	v_fma_f32 v84, -v90, v85, v84
	v_div_fmas_f32 v84, v84, v91, v85
	v_div_fixup_f32 v82, v84, v0, v82
	v_pk_add_f32 v[84:85], v[124:125], 0 op_sel_hi:[1,0]
	v_pk_add_f32 v[82:83], v[82:83], v[120:121] neg_lo:[0,1] neg_hi:[0,1]
	v_pk_add_f32 v[84:85], v[84:85], v[120:121]
	v_cvt_pk_bf16_f32 v82, v82, v83
	v_pk_add_f32 v[90:91], v[84:85], v[118:119]
	global_store_dword v[80:81], v82, off offset:1024
	v_pk_add_f32 v[90:91], v[90:91], v[114:115]
	s_nop 0
	v_cndmask_b32_e64 v85, v91, v85, s[2:3]
	v_cndmask_b32_e64 v84, v90, v84, s[2:3]
	v_pk_add_f32 v[90:91], v[96:97], v[84:85]
	s_nop 0
	v_pk_add_f32 v[90:91], v[94:95], v[90:91]
	s_nop 0
	v_pk_add_f32 v[90:91], v[92:93], v[90:91]
	s_nop 0
	v_pk_add_f32 v[88:89], v[88:89], v[90:91]
	s_nop 0
	v_cndmask_b32_e64 v85, v85, v89, s[4:5]
	v_cndmask_b32_e64 v84, v84, v88, s[4:5]
	v_pk_add_f32 v[88:89], v[102:103], v[84:85]
	s_nop 0
	v_pk_add_f32 v[88:89], v[100:101], v[88:89]
	s_nop 0
	v_pk_add_f32 v[88:89], v[98:99], v[88:89]
	s_nop 0
	v_pk_add_f32 v[88:89], v[104:105], v[88:89]
	s_nop 0
	v_pk_add_f32 v[86:87], v[86:87], v[88:89]
	s_nop 0
	v_pk_add_f32 v[86:87], v[108:109], v[86:87]
	s_nop 0
	v_pk_add_f32 v[86:87], v[106:107], v[86:87]
	s_nop 0
	v_pk_add_f32 v[86:87], v[110:111], v[86:87]
	s_nop 0
	v_cndmask_b32_e64 v85, v85, v87, s[6:7]
	v_div_scale_f32 v87, s[0:1], v1, v1, v85
	v_rcp_f32_e32 v88, v87
	v_cndmask_b32_e64 v80, v84, v86, s[6:7]
	v_fma_f32 v81, -v87, v88, 1.0
	v_fmac_f32_e32 v88, v81, v88
	v_div_scale_f32 v81, vcc, v85, v1, v85
	v_mul_f32_e32 v82, v81, v88
	v_fma_f32 v83, -v87, v82, v81
	v_fmac_f32_e32 v82, v83, v88
	v_div_scale_f32 v83, s[0:1], v0, v0, v80
	v_rcp_f32_e32 v84, v83
	v_fma_f32 v81, -v87, v82, v81
	v_div_fmas_f32 v81, v81, v88, v82
	v_div_fixup_f32 v81, v81, v1, v85
	v_fma_f32 v82, -v83, v84, 1.0
	v_fmac_f32_e32 v84, v82, v84
	v_div_scale_f32 v82, vcc, v80, v0, v80
	v_mul_f32_e32 v85, v82, v84
	v_fma_f32 v86, -v83, v85, v82
	v_fmac_f32_e32 v85, v86, v84
	v_fma_f32 v82, -v83, v85, v82
	v_div_fmas_f32 v82, v82, v84, v85
	v_div_fixup_f32 v80, v82, v0, v80
	v_pk_add_f32 v[80:81], v[80:81], v[124:125] neg_lo:[0,1] neg_hi:[0,1]
	s_mov_b64 s[0:1], 0
	v_cvt_pk_bf16_f32 v80, v80, v81
	global_store_dword v[78:79], v80, off offset:1024
